# attention: waves 4-7 defer the PV product of each key block by one block (3-slot LDS tile ring), so one wave's MFMA overlaps its SIMD partner's softmax VALU
# speedup vs baseline: 1.0092x; 1.0092x over previous
; #define ATT_LOADR(KR, VR, kb) do { KR[0] = *(const u32x4*)(kbase + (size_t)((kb) * 64 + kr0) * 1536); KR[1] = *(const u32x4*)(kbase + (size_t)((kb) * 64 + kr0 + 32) * 1536); \
;         VR[0] = *(const u32x4*)(vbase + (size_t)vr0 * SEQ + (kb) * 64); VR[1] = *(const u32x4*)(vbase + (size_t)(vr0 + 64) * SEQ + (kb) * 64); } while (0)
; #define ATT_STORER(KR, VR, buf) do { LAS unsigned char* kb_ = lds + (buf) * ATT_BUF; LAS unsigned char* vb_ = kb_ + 64 * KP * 2; \
;         *(LAS u32x4*)(kb_ + (kr0 * KP + kc0 * 8) * 2) = KR[0]; *(LAS u32x4*)(kb_ + ((kr0 + 32) * KP + kc0 * 8) * 2) = KR[1]; \
;         *(LAS u32x4*)(vb_ + (vr0 * VP + vc0 * 8) * 2) = VR[0]; *(LAS u32x4*)(vb_ + ((vr0 + 64) * VP + vc0 * 8) * 2) = VR[1]; } while (0)
; __device__ __forceinline__ void attn_phase(const Params& p, int l, int wave, int lane, LAS unsigned char* lds, int early) {
;     ...
;     for (;;) {
;         __syncthreads();
;         if (tid == 0) { int un = 384;
;             if (!(early && __hip_atomic_load(dn, __ATOMIC_RELAXED, __HIP_MEMORY_SCOPE_AGENT) >= 24u)) un = (int)__hip_atomic_fetch_add(aq, 1u, __ATOMIC_RELAXED, __HIP_MEMORY_SCOPE_AGENT);
;             *ubox = un; }
;         __syncthreads();
;         const int u = *ubox;
;         if (u >= 384) break;
;         const int qb = 31 - u / 12, rem = u % 12, b = rem / 6, h = rem % 6;
;         const int q0 = qb * 128, kl = 2 * qb + 1;
;         bf16x8 qf[2][2];
; #pragma unroll
;         for (int rt = 0; rt < 2; ++rt) { const bf16_t* qp = DAQK + (size_t)(b * SEQ + q0 + rq + 16 * rt + qi) * 1536 + h * 128 + sub * 64 + g4 * 8; qf[rt][0] = *(const bf16x8*)qp; qf[rt][1] = *(const bf16x8*)(qp + 32); }
;         f32x4 o[2][8];
; #pragma unroll
;         for (int rt = 0; rt < 2; ++rt)
; #pragma unroll
;             for (int e = 0; e < 8; ++e) o[rt][e] = (f32x4){0.f, 0.f, 0.f, 0.f};
;         float mrun[2] = {-1e30f, -1e30f}, lrun[2] = {0.f, 0.f};
;         const int kr0 = tid >> 4, kc0 = tid & 15;
;         const int vr0 = tid >> 3, vc0 = tid & 7;
;         const bf16_t* kbase = DAQK + (size_t)(b * SEQ) * 1536 + 768 + h * 128 + kc0 * 8;
;         const bf16_t* vbase = VT + (size_t)(b * 768 + h * 128) * SEQ + vc0 * 8;
;         u32x4 kreg[2], vreg[2];
;     ...
;         __syncthreads();
;         ATT_LOADR(kreg, vreg, 0); ATT_STORER(kreg, vreg, 0);
;         __syncthreads();
.LBB0_273:
	s_or_b64 exec, exec, s[22:23]
	v_readlane_b32 s3, v253, 8
	s_waitcnt lgkmcnt(0)
	s_barrier
	v_mov_b32_e32 v0, s3
	ds_read_b32 v0, v0
	s_movk_i32 s22, 0x17f
	s_waitcnt lgkmcnt(0)
	v_cmp_lt_i32_e32 vcc, s22, v0
	v_readfirstlane_b32 s24, v0
	s_mov_b64 s[22:23], -1
	s_cbranch_vccnz .LBB0_264
	s_mul_hi_i32 s22, s24, 0xd5555555
	s_lshr_b32 s23, s22, 31
	s_ashr_i32 s22, s22, 1
	s_add_i32 s28, s22, s23
	s_mul_hi_i32 s22, s24, 0x2aaaaaab
	s_lshr_b32 s23, s22, 31
	s_lshr_b32 s22, s22, 1
	s_add_i32 s22, s22, s23
	s_mul_i32 s22, s22, 12
	s_sub_i32 s22, s24, s22
	s_bfe_i32 s23, s22, 0x80000
	s_mul_i32 s23, s23, 43
	s_bfe_u32 s24, s23, 0x1000f
	s_bfe_u32 s23, s23, 0x80008
	s_add_i32 s23, s23, s24
	s_add_i32 s29, s28, 31
	s_sext_i32_i8 s35, s23
	s_mul_i32 s23, s23, 6
	s_sub_i32 s22, s22, s23
	s_lshl_b32 s23, s29, 7
	s_lshl_b32 s24, s35, 12
	s_sext_i32_i8 s22, s22
	s_add_i32 s24, s24, s23
	v_or_b32_e32 v156, s24, v216
	s_lshl_b32 s24, s22, 7
	s_ashr_i32 s25, s24, 31
	s_lshl_b64 s[22:23], s[24:25], 1
	v_lshl_add_u64 v[0:1], v[130:131], 0, s[22:23]
	s_movk_i32 s3, 0xc00
	v_or_b32_e32 v154, 16, v156
	v_mad_i64_i32 v[2:3], s[26:27], v156, s3, v[0:1]
	v_mad_i64_i32 v[0:1], s[26:27], v154, s3, v[0:1]
	s_mul_i32 s26, s35, 0x600000
	s_ashr_i32 s27, s26, 31
	s_lshl_b32 s33, s29, 1
	s_lshl_b64 s[26:27], s[26:27], 1
	v_readlane_b32 s36, v251, 50
	v_readlane_b32 s37, v251, 51
	s_add_u32 s25, s36, s26
	s_addc_u32 s27, s37, s27
	s_add_u32 s26, s25, s22
	s_mul_i32 s25, s35, 0x300
	s_addc_u32 s27, s27, s23
	s_add_i32 s24, s25, s24
	s_ashr_i32 s25, s24, 31
	s_lshl_b64 s[24:25], s[24:25], 13
	global_load_dwordx4 v[64:67], v[2:3], off
	global_load_dwordx4 v[68:71], v[2:3], off offset:64
	global_load_dwordx4 v[72:75], v[0:1], off
	global_load_dwordx4 v[76:79], v[0:1], off offset:64
	v_lshl_add_u64 v[158:159], s[26:27], 0, v[136:137]
	v_lshl_add_u64 v[0:1], v[132:133], 0, s[24:25]
	v_lshl_add_u64 v[2:3], v[158:159], 0, v[134:135]
	v_lshl_add_u64 v[160:161], v[0:1], 0, v[146:147]
	s_barrier
	global_load_dwordx4 v[80:83], v[2:3], off offset:1536
	global_load_dwordx4 v[88:91], v[160:161], off
	v_lshl_add_u64 v[2:3], v[158:159], 0, v[144:145]
	global_load_dwordx4 v[84:87], v[2:3], off offset:1536
	v_lshl_add_u64 v[162:163], v[0:1], 0, v[148:149]
	global_load_dwordx4 v[92:95], v[162:163], off
	v_add_u32_e32 v0, 0, v170
	v_mov_b32_e32 v20, v137
	v_mov_b32_e32 v21, v137
	v_mov_b32_e32 v22, v137
	v_mov_b32_e32 v23, v137
	s_lshl_b32 s24, s28, 7
	v_mov_b64_e32 v[30:31], v[22:23]
	v_mov_b64_e32 v[34:35], v[22:23]
	v_mov_b64_e32 v[38:39], v[22:23]
	v_mov_b64_e32 v[42:43], v[22:23]
	v_mov_b64_e32 v[46:47], v[22:23]
	v_mov_b64_e32 v[50:51], v[22:23]
	v_mov_b64_e32 v[54:55], v[22:23]
	v_mov_b64_e32 v[58:59], v[22:23]
	v_mov_b64_e32 v[62:63], v[22:23]
	v_mov_b64_e32 v[26:27], v[22:23]
	v_mov_b64_e32 v[16:17], v[20:21]
	v_mov_b64_e32 v[12:13], v[20:21]
	v_mov_b64_e32 v[8:9], v[20:21]
	v_mov_b64_e32 v[4:5], v[20:21]
	v_ashrrev_i32_e32 v157, 31, v156
	v_ashrrev_i32_e32 v155, 31, v154
	s_or_b32 s35, s30, s24
	s_mov_b32 s24, 0
	v_mov_b32_e32 v217, 0
	v_mov_b32_e32 v220, 0xf149f2ca
	v_mov_b64_e32 v[28:29], v[20:21]
	v_mov_b64_e32 v[32:33], v[20:21]
	v_mov_b64_e32 v[36:37], v[20:21]
	v_mov_b64_e32 v[40:41], v[20:21]
	v_mov_b64_e32 v[44:45], v[20:21]
	v_mov_b64_e32 v[48:49], v[20:21]
	v_mov_b64_e32 v[52:53], v[20:21]
	v_mov_b64_e32 v[56:57], v[20:21]
	v_mov_b64_e32 v[60:61], v[20:21]
	v_mov_b32_e32 v128, 0xf149f2ca
	v_mov_b32_e32 v218, 0
	v_mov_b64_e32 v[24:25], v[20:21]
	v_mov_b64_e32 v[18:19], v[22:23]
	v_mov_b64_e32 v[14:15], v[22:23]
	v_mov_b64_e32 v[10:11], v[22:23]
	v_mov_b64_e32 v[6:7], v[22:23]
	s_mov_b32 s36, 0
	s_mov_b32 s100, 0
	v_readfirstlane_b32 s101, v182
	s_nop 0
	s_lshr_b32 s101, s101, 8
	s_waitcnt vmcnt(3)
	ds_write_b128 v0, v[80:83]
	v_add_u32_e32 v0, 0, v171
	s_waitcnt vmcnt(1)
	ds_write_b128 v0, v[84:87]
	v_add_u32_e32 v0, 0, v172
	ds_write_b128 v0, v[88:91] offset:17408
	v_add_u32_e32 v0, 0, v173
	s_waitcnt vmcnt(0)
	ds_write_b128 v0, v[92:95] offset:17408
	v_mov_b64_e32 v[0:1], v[20:21]
	v_mov_b64_e32 v[2:3], v[22:23]
	s_waitcnt lgkmcnt(0)
	s_barrier

.LBB0_277:
	s_cmp_eq_u32 s101, 1
	s_cbranch_scc0 .Latt_no_early
	s_cmp_eq_u32 s36, 0
	s_cbranch_scc1 .Latt_no_early
	s_sub_i32 s25, s100, 0x8c00
	s_cmp_lt_i32 s25, 0
	s_cselect_b32 s25, 0x11800, s25
	s_setprio 1
	v_add_u32_e32 v142, s25, v168
	v_add_u32_e32 v231, v142, v211
	v_add_u32_e32 v243, v142, v212
	v_add_u32_e32 v142, v142, v213
	v_add_u32_e32 v240, 0x4000, v231
	v_add_u32_e32 v241, 0x4800, v231
	v_add_u32_e32 v242, 0x5000, v231
	v_add_u32_e32 v244, 0x6800, v231
	v_add_u32_e32 v245, 0x7000, v231
	v_add_u32_e32 v231, 0x7800, v231
	v_add_u32_e32 v243, 0x4000, v243
	v_add_u32_e32 v142, 0x4000, v142
	ds_read2_b64 v[236:239], v240 offset0:128 offset1:132
	ds_read2_b64 v[184:187], v241 offset0:160 offset1:164
	ds_read2_b64 v[188:191], v242 offset0:192 offset1:196
	ds_read2_b64 v[196:199], v243 offset0:128 offset1:132
	s_waitcnt lgkmcnt(3)
	v_mfma_f32_16x16x32_bf16 v[60:63], v[236:239], v[116:119], v[60:63]
	v_mfma_f32_16x16x32_bf16 v[28:31], v[236:239], v[138:141], v[28:31]
	ds_read2_b64 v[236:239], v244 offset1:4
	s_waitcnt lgkmcnt(3)
	v_mfma_f32_16x16x32_bf16 v[56:59], v[184:187], v[116:119], v[56:59]
	v_mfma_f32_16x16x32_bf16 v[20:23], v[184:187], v[138:141], v[20:23]
	ds_read2_b64 v[184:187], v245 offset0:32 offset1:36
	s_waitcnt lgkmcnt(3)
	v_mfma_f32_16x16x32_bf16 v[52:55], v[188:191], v[116:119], v[52:55]
	v_mfma_f32_16x16x32_bf16 v[24:27], v[188:191], v[138:141], v[24:27]
	ds_read2_b64 v[188:191], v231 offset0:64 offset1:68
	s_waitcnt lgkmcnt(3)
	v_mfma_f32_16x16x32_bf16 v[48:51], v[196:199], v[116:119], v[48:51]
	v_mfma_f32_16x16x32_bf16 v[16:19], v[196:199], v[138:141], v[16:19]
	ds_read2_b64 v[196:199], v142 offset0:128 offset1:132
	s_waitcnt lgkmcnt(3)
	v_mfma_f32_16x16x32_bf16 v[44:47], v[236:239], v[116:119], v[44:47]
	v_mfma_f32_16x16x32_bf16 v[12:15], v[236:239], v[138:141], v[12:15]
	ds_read2_b64 v[236:239], v240 offset0:136 offset1:140
	s_waitcnt lgkmcnt(3)
	v_mfma_f32_16x16x32_bf16 v[40:43], v[184:187], v[116:119], v[40:43]
	v_mfma_f32_16x16x32_bf16 v[8:11], v[184:187], v[138:141], v[8:11]
	ds_read2_b64 v[184:187], v241 offset0:168 offset1:172
	s_waitcnt lgkmcnt(3)
	v_mfma_f32_16x16x32_bf16 v[36:39], v[188:191], v[116:119], v[36:39]
	v_mfma_f32_16x16x32_bf16 v[4:7], v[188:191], v[138:141], v[4:7]
	ds_read2_b64 v[188:191], v242 offset0:200 offset1:204
	s_waitcnt lgkmcnt(3)
	v_mfma_f32_16x16x32_bf16 v[32:35], v[196:199], v[116:119], v[32:35]
	v_mfma_f32_16x16x32_bf16 v[0:3], v[196:199], v[138:141], v[0:3]
	ds_read2_b64 v[196:199], v243 offset0:136 offset1:140
	s_waitcnt lgkmcnt(3)
	v_mfma_f32_16x16x32_bf16 v[60:63], v[236:239], v[112:115], v[60:63]
	v_mfma_f32_16x16x32_bf16 v[28:31], v[236:239], v[232:235], v[28:31]
	ds_read2_b64 v[236:239], v244 offset0:8 offset1:12
	s_waitcnt lgkmcnt(3)
	v_mfma_f32_16x16x32_bf16 v[56:59], v[184:187], v[112:115], v[56:59]
	v_mfma_f32_16x16x32_bf16 v[20:23], v[184:187], v[232:235], v[20:23]
	ds_read2_b64 v[184:187], v245 offset0:40 offset1:44
	s_waitcnt lgkmcnt(3)
	v_mfma_f32_16x16x32_bf16 v[52:55], v[188:191], v[112:115], v[52:55]
	v_mfma_f32_16x16x32_bf16 v[24:27], v[188:191], v[232:235], v[24:27]
	ds_read2_b64 v[188:191], v231 offset0:72 offset1:76
	s_waitcnt lgkmcnt(3)
	v_mfma_f32_16x16x32_bf16 v[48:51], v[196:199], v[112:115], v[48:51]
	v_mfma_f32_16x16x32_bf16 v[16:19], v[196:199], v[232:235], v[16:19]
	ds_read2_b64 v[196:199], v142 offset0:136 offset1:140
	s_waitcnt lgkmcnt(3)
	v_mfma_f32_16x16x32_bf16 v[44:47], v[236:239], v[112:115], v[44:47]
	v_mfma_f32_16x16x32_bf16 v[12:15], v[236:239], v[232:235], v[12:15]
	s_waitcnt lgkmcnt(2)
	v_mfma_f32_16x16x32_bf16 v[40:43], v[184:187], v[112:115], v[40:43]
	v_mfma_f32_16x16x32_bf16 v[8:11], v[184:187], v[232:235], v[8:11]
	s_waitcnt lgkmcnt(1)
	v_mfma_f32_16x16x32_bf16 v[36:39], v[188:191], v[112:115], v[36:39]
	v_mfma_f32_16x16x32_bf16 v[4:7], v[188:191], v[232:235], v[4:7]
	s_waitcnt lgkmcnt(0)
	v_mfma_f32_16x16x32_bf16 v[32:35], v[196:199], v[112:115], v[32:35]
	v_mfma_f32_16x16x32_bf16 v[0:3], v[196:199], v[232:235], v[0:3]
	s_setprio 0
.Latt_no_early:
	s_mov_b32 s25, s100
	s_setprio 1
	s_add_i32 s37, s31, s25
	v_add_u32_e32 v124, s37, v166
	v_add_u32_e32 v120, v124, v175
	ds_read_b128 v[96:99], v120
	ds_read_b128 v[100:103], v120 offset:64
	v_add_u32_e32 v124, v124, v176
	s_waitcnt lgkmcnt(1)
	v_mfma_f32_16x16x32_bf16 v[104:107], v[96:99], v[64:67], 0
	v_mfma_f32_16x16x32_bf16 v[96:99], v[96:99], v[72:75], 0
	s_waitcnt lgkmcnt(0)
	v_mfma_f32_16x16x32_bf16 v[112:115], v[100:103], v[68:71], v[104:107]
	v_mfma_f32_16x16x32_bf16 v[96:99], v[100:103], v[76:79], v[96:99]
	ds_read_b128 v[100:103], v120 offset:4352
	s_nop 2
	ds_read_b128 v[104:107], v120 offset:4416
	s_waitcnt lgkmcnt(1)
	v_mfma_f32_16x16x32_bf16 v[108:111], v[100:103], v[64:67], 0
	v_mfma_f32_16x16x32_bf16 v[100:103], v[100:103], v[72:75], 0
	s_waitcnt lgkmcnt(0)
	v_mfma_f32_16x16x32_bf16 v[116:119], v[104:107], v[68:71], v[108:111]
	v_mfma_f32_16x16x32_bf16 v[100:103], v[104:107], v[76:79], v[100:103]
	ds_read_b128 v[104:107], v120 offset:8704
	s_nop 2
	ds_read_b128 v[108:111], v120 offset:8768
	s_waitcnt lgkmcnt(1)
	v_mfma_f32_16x16x32_bf16 v[120:123], v[104:107], v[64:67], 0
	v_mfma_f32_16x16x32_bf16 v[104:107], v[104:107], v[72:75], 0
	s_waitcnt lgkmcnt(0)
	v_mfma_f32_16x16x32_bf16 v[120:123], v[108:111], v[68:71], v[120:123]
	v_mfma_f32_16x16x32_bf16 v[104:107], v[108:111], v[76:79], v[104:107]
	ds_read_b128 v[108:111], v124
	ds_read_b128 v[138:141], v124 offset:64
	s_waitcnt lgkmcnt(1)
	v_mfma_f32_16x16x32_bf16 v[124:127], v[108:111], v[64:67], 0
	v_mfma_f32_16x16x32_bf16 v[108:111], v[108:111], v[72:75], 0
	s_waitcnt lgkmcnt(0)
	v_mfma_f32_16x16x32_bf16 v[124:127], v[138:141], v[68:71], v[124:127]
	v_mfma_f32_16x16x32_bf16 v[108:111], v[138:141], v[76:79], v[108:111]
	s_setprio 0
	s_add_i32 s37, s35, 0xf80
	s_cmp_gt_i32 s37, 62
	s_cbranch_scc1 .LBB0_279
	v_add_u32_e32 v138, s35, v164
	v_add_u32_e32 v139, 0xf80, v138
	s_mov_b32 s3, 0xf149f2ca
	v_mov_b32_e32 v138, s3
	v_cmp_gt_i32_e32 vcc, v150, v139
	s_nop 1
	v_cndmask_b32_e32 v138, v112, v138, vcc
	v_cmp_lt_i32_e32 vcc, v150, v139
	s_nop 1
	v_cndmask_b32_e32 v112, v138, v112, vcc
	v_cndmask_b32_e32 v113, v195, v113, vcc
	v_cmp_le_i32_e32 vcc, v177, v139
	v_mov_b32_e32 v138, s3
	s_nop 0
	v_cndmask_b32_e32 v114, v195, v114, vcc
	v_cmp_le_i32_e32 vcc, v178, v139
	s_nop 1
	v_cndmask_b32_e32 v115, v195, v115, vcc
	v_cmp_gt_i32_e32 vcc, v179, v139
	s_nop 1
	v_cndmask_b32_e32 v116, v116, v138, vcc
	v_cmp_le_i32_e32 vcc, v180, v139
	s_nop 1
	v_cndmask_b32_e32 v117, v195, v117, vcc
	v_cmp_le_i32_e32 vcc, v181, v139
	s_nop 1
	v_cndmask_b32_e32 v118, v195, v118, vcc
	v_cmp_le_i32_e32 vcc, v202, v139
	s_nop 1
	v_cndmask_b32_e32 v119, v195, v119, vcc
	v_cmp_gt_i32_e32 vcc, v203, v139
	s_nop 1
	v_cndmask_b32_e32 v120, v120, v138, vcc
	v_cmp_le_i32_e32 vcc, v204, v139
	s_nop 1
	v_cndmask_b32_e32 v121, v195, v121, vcc
	v_cmp_le_i32_e32 vcc, v205, v139
	s_nop 1
	v_cndmask_b32_e32 v122, v195, v122, vcc
	v_cmp_le_i32_e32 vcc, v206, v139
	s_nop 1
	v_cndmask_b32_e32 v123, v195, v123, vcc
	v_cmp_gt_i32_e32 vcc, v207, v139
	s_nop 1
	v_cndmask_b32_e32 v124, v124, v138, vcc
	v_cmp_le_i32_e32 vcc, v208, v139
	s_nop 1
	v_cndmask_b32_e32 v125, v195, v125, vcc
	v_cmp_le_i32_e32 vcc, v209, v139
	s_nop 1
	v_cndmask_b32_e32 v126, v195, v126, vcc
	v_cmp_le_i32_e32 vcc, v210, v139
	s_nop 1
	v_cndmask_b32_e32 v127, v195, v127, vcc

.LBB0_285:
	v_sub_f32_e32 v96, v96, v230
	v_sub_f32_e32 v97, v97, v230
	v_sub_f32_e32 v98, v98, v230
	v_sub_f32_e32 v99, v99, v230
	v_sub_f32_e32 v100, v100, v230
	v_sub_f32_e32 v101, v101, v230
	v_sub_f32_e32 v102, v102, v230
	v_sub_f32_e32 v103, v103, v230
	v_sub_f32_e32 v104, v104, v230
	v_sub_f32_e32 v105, v105, v230
	v_sub_f32_e32 v106, v106, v230
	v_sub_f32_e32 v107, v107, v230
	v_sub_f32_e32 v108, v108, v230
	v_sub_f32_e32 v109, v109, v230
	v_sub_f32_e32 v110, v110, v230
	v_sub_f32_e32 v111, v111, v230
	v_exp_f32_e32 v96, v96
	v_exp_f32_e32 v97, v97
	v_exp_f32_e32 v98, v98
	v_exp_f32_e32 v99, v99
	v_exp_f32_e32 v100, v100
	v_exp_f32_e32 v101, v101
	v_exp_f32_e32 v102, v102
	v_exp_f32_e32 v103, v103
	v_exp_f32_e32 v104, v104
	v_exp_f32_e32 v105, v105
	v_exp_f32_e32 v106, v106
	v_exp_f32_e32 v107, v107
	v_exp_f32_e32 v108, v108
	v_exp_f32_e32 v109, v109
	v_exp_f32_e32 v110, v110
	v_exp_f32_e32 v111, v111
	v_cvt_pk_bf16_f32 v138, v96, v97
	v_cvt_pk_bf16_f32 v139, v98, v99
	v_cvt_pk_bf16_f32 v140, v100, v101
	v_cvt_pk_bf16_f32 v141, v102, v103
	v_cvt_pk_bf16_f32 v232, v104, v105
	v_cvt_pk_bf16_f32 v233, v106, v107
	v_cvt_pk_bf16_f32 v234, v108, v109
	v_cvt_pk_bf16_f32 v235, v110, v111
	s_cmp_eq_u32 s101, 1
	s_cbranch_scc1 .Latt_skip_pv
	s_setprio 1
	v_add_u32_e32 v220, s25, v168
	v_add_u32_e32 v231, v220, v211
	v_add_u32_e32 v243, v220, v212
	v_add_u32_e32 v220, v220, v213
	v_add_u32_e32 v240, 0x4000, v231
	v_add_u32_e32 v241, 0x4800, v231
	v_add_u32_e32 v242, 0x5000, v231
	v_add_u32_e32 v244, 0x6800, v231
	v_add_u32_e32 v245, 0x7000, v231
	v_add_u32_e32 v231, 0x7800, v231
	v_add_u32_e32 v243, 0x4000, v243
	v_add_u32_e32 v220, 0x4000, v220
	ds_read2_b64 v[236:239], v240 offset0:128 offset1:132
	ds_read2_b64 v[184:187], v241 offset0:160 offset1:164
	ds_read2_b64 v[188:191], v242 offset0:192 offset1:196
	ds_read2_b64 v[196:199], v243 offset0:128 offset1:132
	s_waitcnt lgkmcnt(3)
	v_mfma_f32_16x16x32_bf16 v[60:63], v[236:239], v[116:119], v[60:63]
	v_mfma_f32_16x16x32_bf16 v[28:31], v[236:239], v[138:141], v[28:31]
	ds_read2_b64 v[236:239], v244 offset1:4
	s_waitcnt lgkmcnt(3)
	v_mfma_f32_16x16x32_bf16 v[56:59], v[184:187], v[116:119], v[56:59]
	v_mfma_f32_16x16x32_bf16 v[20:23], v[184:187], v[138:141], v[20:23]
	ds_read2_b64 v[184:187], v245 offset0:32 offset1:36
	s_waitcnt lgkmcnt(3)
	v_mfma_f32_16x16x32_bf16 v[52:55], v[188:191], v[116:119], v[52:55]
	v_mfma_f32_16x16x32_bf16 v[24:27], v[188:191], v[138:141], v[24:27]
	ds_read2_b64 v[188:191], v231 offset0:64 offset1:68
	s_waitcnt lgkmcnt(3)
	v_mfma_f32_16x16x32_bf16 v[48:51], v[196:199], v[116:119], v[48:51]
	v_mfma_f32_16x16x32_bf16 v[16:19], v[196:199], v[138:141], v[16:19]
	ds_read2_b64 v[196:199], v220 offset0:128 offset1:132
	s_waitcnt lgkmcnt(3)
	v_mfma_f32_16x16x32_bf16 v[44:47], v[236:239], v[116:119], v[44:47]
	v_mfma_f32_16x16x32_bf16 v[12:15], v[236:239], v[138:141], v[12:15]
	ds_read2_b64 v[236:239], v240 offset0:136 offset1:140
	s_waitcnt lgkmcnt(3)
	v_mfma_f32_16x16x32_bf16 v[40:43], v[184:187], v[116:119], v[40:43]
	v_mfma_f32_16x16x32_bf16 v[8:11], v[184:187], v[138:141], v[8:11]
	ds_read2_b64 v[184:187], v241 offset0:168 offset1:172
	s_waitcnt lgkmcnt(3)
	v_mfma_f32_16x16x32_bf16 v[36:39], v[188:191], v[116:119], v[36:39]
	v_mfma_f32_16x16x32_bf16 v[4:7], v[188:191], v[138:141], v[4:7]
	ds_read2_b64 v[188:191], v242 offset0:200 offset1:204
	s_waitcnt lgkmcnt(3)
	v_mfma_f32_16x16x32_bf16 v[32:35], v[196:199], v[116:119], v[32:35]
	v_mfma_f32_16x16x32_bf16 v[0:3], v[196:199], v[138:141], v[0:3]
	ds_read2_b64 v[196:199], v243 offset0:136 offset1:140
	s_waitcnt lgkmcnt(3)
	v_mfma_f32_16x16x32_bf16 v[60:63], v[236:239], v[112:115], v[60:63]
	v_mfma_f32_16x16x32_bf16 v[28:31], v[236:239], v[232:235], v[28:31]
	ds_read2_b64 v[236:239], v244 offset0:8 offset1:12
	s_waitcnt lgkmcnt(3)
	v_mfma_f32_16x16x32_bf16 v[56:59], v[184:187], v[112:115], v[56:59]
	v_mfma_f32_16x16x32_bf16 v[20:23], v[184:187], v[232:235], v[20:23]
	ds_read2_b64 v[184:187], v245 offset0:40 offset1:44
	s_waitcnt lgkmcnt(3)
	v_mfma_f32_16x16x32_bf16 v[52:55], v[188:191], v[112:115], v[52:55]
	v_mfma_f32_16x16x32_bf16 v[24:27], v[188:191], v[232:235], v[24:27]
	ds_read2_b64 v[188:191], v231 offset0:72 offset1:76
	s_waitcnt lgkmcnt(3)
	v_mfma_f32_16x16x32_bf16 v[48:51], v[196:199], v[112:115], v[48:51]
	v_mfma_f32_16x16x32_bf16 v[16:19], v[196:199], v[232:235], v[16:19]
	ds_read2_b64 v[196:199], v220 offset0:136 offset1:140
	s_waitcnt lgkmcnt(3)
	v_mfma_f32_16x16x32_bf16 v[44:47], v[236:239], v[112:115], v[44:47]
	v_mfma_f32_16x16x32_bf16 v[12:15], v[236:239], v[232:235], v[12:15]
	s_waitcnt lgkmcnt(2)
	v_mfma_f32_16x16x32_bf16 v[40:43], v[184:187], v[112:115], v[40:43]
	v_mfma_f32_16x16x32_bf16 v[8:11], v[184:187], v[232:235], v[8:11]
	s_waitcnt lgkmcnt(1)
	v_mfma_f32_16x16x32_bf16 v[36:39], v[188:191], v[112:115], v[36:39]
	v_mfma_f32_16x16x32_bf16 v[4:7], v[188:191], v[232:235], v[4:7]
	s_waitcnt lgkmcnt(0)
	v_mfma_f32_16x16x32_bf16 v[32:35], v[196:199], v[112:115], v[32:35]
	v_mfma_f32_16x16x32_bf16 v[0:3], v[196:199], v[232:235], v[0:3]
	s_setprio 0
.Latt_skip_pv:
	s_andn2_b64 vcc, exec, s[28:29]
	s_cbranch_vccnz .LBB0_287
	s_add_i32 s25, s100, 0x8c00
	s_cmp_eq_u32 s25, 0x1a400
	s_cselect_b32 s25, 0, s25
	v_add_u32_e32 v142, s25, v170
	v_add_u32_e32 v183, s25, v171
	v_add_u32_e32 v192, s25, v172
	v_add_u32_e32 v193, s25, v173
	s_waitcnt vmcnt(3)
	ds_write_b128 v142, v[80:83]
	s_waitcnt vmcnt(2)
	ds_write_b128 v183, v[84:87]
	s_waitcnt vmcnt(1)
	ds_write_b128 v192, v[88:91] offset:17408
	s_waitcnt vmcnt(0)
	ds_write_b128 v193, v[92:95] offset:17408
; #define ATT_LOADR(KR, VR, kb) do { KR[0] = *(const u32x4*)(kbase + (size_t)((kb) * 64 + kr0) * 1536); KR[1] = *(const u32x4*)(kbase + (size_t)((kb) * 64 + kr0 + 32) * 1536); \
;         VR[0] = *(const u32x4*)(vbase + (size_t)vr0 * SEQ + (kb) * 64); VR[1] = *(const u32x4*)(vbase + (size_t)(vr0 + 64) * SEQ + (kb) * 64); } while (0)
; #define ATT_STORER(KR, VR, buf) do { LAS unsigned char* kb_ = lds + (buf) * ATT_BUF; LAS unsigned char* vb_ = kb_ + 64 * KP * 2; \
;         *(LAS u32x4*)(kb_ + (kr0 * KP + kc0 * 8) * 2) = KR[0]; *(LAS u32x4*)(kb_ + ((kr0 + 32) * KP + kc0 * 8) * 2) = KR[1]; \
;         *(LAS u32x4*)(vb_ + (vr0 * VP + vc0 * 8) * 2) = VR[0]; *(LAS u32x4*)(vb_ + ((vr0 + 64) * VP + vc0 * 8) * 2) = VR[1]; } while (0)
; __device__ __forceinline__ void attn_phase(const Params& p, int l, int wave, int lane, LAS unsigned char* lds, int early) {
;     ...
;         for (int kb = 0; kb <= kl; ++kb) {
;             if (kb < kl) ATT_LOADR(kreg, vreg, kb + 1);
;             ATT_COMPUTE(kb);
;             if (kb < kl) ATT_STORER(kreg, vreg, (kb + 1) & 1);
;             __syncthreads();
;         }
.LBB0_287:
	v_add_f32_e32 v96, 0, v96
	v_add_f32_e32 v96, v97, v96
	v_add_f32_e32 v97, 0, v221
	v_add_f32_e32 v97, v222, v97
	v_add_f32_e32 v96, v98, v96
	v_add_f32_e32 v97, v223, v97
	v_add_f32_e32 v96, v99, v96
	v_add_f32_e32 v97, v224, v97
	v_add_f32_e32 v96, v100, v96
	v_add_f32_e32 v97, v225, v97
	v_add_f32_e32 v96, v101, v96
	v_add_f32_e32 v97, v226, v97
	v_add_f32_e32 v96, v102, v96
	v_add_f32_e32 v97, v227, v97
	v_add_f32_e32 v96, v103, v96
	v_add_f32_e32 v97, v228, v97
	v_add_f32_e32 v96, v104, v96
	v_add_f32_e32 v97, v229, v97
	v_add_f32_e32 v96, v105, v96
	v_add_f32_e32 v97, v121, v97
	v_add_f32_e32 v96, v106, v96
	v_add_f32_e32 v97, v122, v97
	v_add_f32_e32 v96, v107, v96
	v_add_f32_e32 v97, v123, v97
	v_add_f32_e32 v96, v108, v96
	v_add_f32_e32 v97, v124, v97
	v_add_f32_e32 v96, v109, v96
	v_add_f32_e32 v97, v125, v97
	v_add_f32_e32 v96, v110, v96
	v_add_f32_e32 v97, v126, v97
	v_add_f32_e32 v96, v111, v96
	v_add_f32_e32 v97, v127, v97
	v_fmac_f32_e32 v96, v217, v120
	v_fmac_f32_e32 v97, v218, v128
	s_add_i32 s36, s36, 1
	s_add_i32 s100, s100, 0x8c00
	s_cmp_eq_u32 s100, 0x1a400
	s_cselect_b32 s100, 0, s100
	s_add_i32 s24, s24, 64
	s_sub_i32 s35, s35, 64
	s_and_b64 vcc, exec, s[26:27]
	s_waitcnt lgkmcnt(0)
	s_barrier
	s_cbranch_vccnz .LBB0_289
	v_mov_b32_e32 v220, v230
	v_mov_b32_e32 v128, v219
	v_mov_b32_e32 v217, v96
	v_mov_b32_e32 v218, v97
	s_branch .LBB0_275
.LBB0_289:
	s_cmp_eq_u32 s101, 1
	s_cbranch_scc0 .Latt_no_final
	s_sub_i32 s25, s100, 0x8c00
	s_cmp_lt_i32 s25, 0
	s_cselect_b32 s25, 0x11800, s25
	s_setprio 1
	v_add_u32_e32 v142, s25, v168
	v_add_u32_e32 v231, v142, v211
	v_add_u32_e32 v243, v142, v212
	v_add_u32_e32 v142, v142, v213
	v_add_u32_e32 v240, 0x4000, v231
	v_add_u32_e32 v241, 0x4800, v231
	v_add_u32_e32 v242, 0x5000, v231
	v_add_u32_e32 v244, 0x6800, v231
	v_add_u32_e32 v245, 0x7000, v231
	v_add_u32_e32 v231, 0x7800, v231
	v_add_u32_e32 v243, 0x4000, v243
	v_add_u32_e32 v142, 0x4000, v142
	ds_read2_b64 v[236:239], v240 offset0:128 offset1:132
	ds_read2_b64 v[184:187], v241 offset0:160 offset1:164
	ds_read2_b64 v[188:191], v242 offset0:192 offset1:196
	ds_read2_b64 v[196:199], v243 offset0:128 offset1:132
	s_waitcnt lgkmcnt(3)
	v_mfma_f32_16x16x32_bf16 v[60:63], v[236:239], v[116:119], v[60:63]
	v_mfma_f32_16x16x32_bf16 v[28:31], v[236:239], v[138:141], v[28:31]
	ds_read2_b64 v[236:239], v244 offset1:4
	s_waitcnt lgkmcnt(3)
	v_mfma_f32_16x16x32_bf16 v[56:59], v[184:187], v[116:119], v[56:59]
	v_mfma_f32_16x16x32_bf16 v[20:23], v[184:187], v[138:141], v[20:23]
	ds_read2_b64 v[184:187], v245 offset0:32 offset1:36
	s_waitcnt lgkmcnt(3)
	v_mfma_f32_16x16x32_bf16 v[52:55], v[188:191], v[116:119], v[52:55]
	v_mfma_f32_16x16x32_bf16 v[24:27], v[188:191], v[138:141], v[24:27]
	ds_read2_b64 v[188:191], v231 offset0:64 offset1:68
	s_waitcnt lgkmcnt(3)
	v_mfma_f32_16x16x32_bf16 v[48:51], v[196:199], v[116:119], v[48:51]
	v_mfma_f32_16x16x32_bf16 v[16:19], v[196:199], v[138:141], v[16:19]
	ds_read2_b64 v[196:199], v142 offset0:128 offset1:132
	s_waitcnt lgkmcnt(3)
	v_mfma_f32_16x16x32_bf16 v[44:47], v[236:239], v[116:119], v[44:47]
	v_mfma_f32_16x16x32_bf16 v[12:15], v[236:239], v[138:141], v[12:15]
	ds_read2_b64 v[236:239], v240 offset0:136 offset1:140
	s_waitcnt lgkmcnt(3)
	v_mfma_f32_16x16x32_bf16 v[40:43], v[184:187], v[116:119], v[40:43]
	v_mfma_f32_16x16x32_bf16 v[8:11], v[184:187], v[138:141], v[8:11]
	ds_read2_b64 v[184:187], v241 offset0:168 offset1:172
	s_waitcnt lgkmcnt(3)
	v_mfma_f32_16x16x32_bf16 v[36:39], v[188:191], v[116:119], v[36:39]
	v_mfma_f32_16x16x32_bf16 v[4:7], v[188:191], v[138:141], v[4:7]
	ds_read2_b64 v[188:191], v242 offset0:200 offset1:204
	s_waitcnt lgkmcnt(3)
	v_mfma_f32_16x16x32_bf16 v[32:35], v[196:199], v[116:119], v[32:35]
	v_mfma_f32_16x16x32_bf16 v[0:3], v[196:199], v[138:141], v[0:3]
	ds_read2_b64 v[196:199], v243 offset0:136 offset1:140
	s_waitcnt lgkmcnt(3)
	v_mfma_f32_16x16x32_bf16 v[60:63], v[236:239], v[112:115], v[60:63]
	v_mfma_f32_16x16x32_bf16 v[28:31], v[236:239], v[232:235], v[28:31]
	ds_read2_b64 v[236:239], v244 offset0:8 offset1:12
	s_waitcnt lgkmcnt(3)
	v_mfma_f32_16x16x32_bf16 v[56:59], v[184:187], v[112:115], v[56:59]
	v_mfma_f32_16x16x32_bf16 v[20:23], v[184:187], v[232:235], v[20:23]
	ds_read2_b64 v[184:187], v245 offset0:40 offset1:44
	s_waitcnt lgkmcnt(3)
	v_mfma_f32_16x16x32_bf16 v[52:55], v[188:191], v[112:115], v[52:55]
	v_mfma_f32_16x16x32_bf16 v[24:27], v[188:191], v[232:235], v[24:27]
	ds_read2_b64 v[188:191], v231 offset0:72 offset1:76
	s_waitcnt lgkmcnt(3)
	v_mfma_f32_16x16x32_bf16 v[48:51], v[196:199], v[112:115], v[48:51]
	v_mfma_f32_16x16x32_bf16 v[16:19], v[196:199], v[232:235], v[16:19]
	ds_read2_b64 v[196:199], v142 offset0:136 offset1:140
	s_waitcnt lgkmcnt(3)
	v_mfma_f32_16x16x32_bf16 v[44:47], v[236:239], v[112:115], v[44:47]
	v_mfma_f32_16x16x32_bf16 v[12:15], v[236:239], v[232:235], v[12:15]
	s_waitcnt lgkmcnt(2)
	v_mfma_f32_16x16x32_bf16 v[40:43], v[184:187], v[112:115], v[40:43]
	v_mfma_f32_16x16x32_bf16 v[8:11], v[184:187], v[232:235], v[8:11]
	s_waitcnt lgkmcnt(1)
	v_mfma_f32_16x16x32_bf16 v[36:39], v[188:191], v[112:115], v[36:39]
	v_mfma_f32_16x16x32_bf16 v[4:7], v[188:191], v[232:235], v[4:7]
	s_waitcnt lgkmcnt(0)
	v_mfma_f32_16x16x32_bf16 v[32:35], v[196:199], v[112:115], v[32:35]
	v_mfma_f32_16x16x32_bf16 v[0:3], v[196:199], v[232:235], v[0:3]
	s_setprio 0
; #define LAS __attribute__((address_space(3)))
; #define SHX(v, a) __builtin_bit_cast(float, __builtin_amdgcn_ds_bpermute((a), __builtin_bit_cast(int, (v))))
; __device__ __forceinline__ void attn_phase(const Params& p, int l, int wave, int lane, LAS unsigned char* lds, int early) {
;     ...
;         float inv[2];
; #pragma unroll
;         for (int rt = 0; rt < 2; ++rt) { float lt = lrun[rt]; lt += SHX(lt, x16); lt += SHX(lt, x32); inv[rt] = 1.0f / lt; }
;         if (sub == 1) {
; #pragma unroll
;             for (int rt = 0; rt < 2; ++rt) { LAS float* ox = (LAS float*)lds + ((wave & 3) * 2 + rt) * 2048;
; #pragma unroll
;                 for (int e = 0; e < 8; ++e)
; #pragma unroll
;                     for (int i = 0; i < 4; ++i) ox[(16 * e + 4 * g4 + i) * 16 + qi] = o[rt][e][i] * inv[rt]; }
.Latt_no_final:
	s_barrier
	ds_bpermute_b32 v64, v165, v97
	s_waitcnt lgkmcnt(0)
	v_add_f32_e32 v64, v97, v64
	ds_bpermute_b32 v65, v167, v64
	s_waitcnt lgkmcnt(0)
	v_add_f32_e32 v64, v64, v65
	v_div_scale_f32 v65, s[24:25], v64, v64, 1.0
	v_rcp_f32_e32 v66, v65
	s_nop 0
	v_fma_f32 v67, -v65, v66, 1.0
	v_fmac_f32_e32 v66, v67, v66
	v_div_scale_f32 v67, vcc, 1.0, v64, 1.0
	v_mul_f32_e32 v68, v67, v66
	v_fma_f32 v69, -v65, v68, v67
	v_fmac_f32_e32 v68, v69, v66
	v_fma_f32 v65, -v65, v68, v67
	v_div_fmas_f32 v65, v65, v66, v68
	v_div_fixup_f32 v66, v65, v64, 1.0
	ds_bpermute_b32 v64, v165, v96
	s_waitcnt lgkmcnt(0)
	v_add_f32_e32 v64, v96, v64
	ds_bpermute_b32 v65, v167, v64
	s_waitcnt lgkmcnt(0)
	v_add_f32_e32 v64, v64, v65
	v_div_scale_f32 v65, s[24:25], v64, v64, 1.0
	v_rcp_f32_e32 v67, v65
	s_nop 0
	v_fma_f32 v68, -v65, v67, 1.0
	v_fmac_f32_e32 v67, v68, v67
	v_div_scale_f32 v68, vcc, 1.0, v64, 1.0
	v_mul_f32_e32 v69, v68, v67
	v_fma_f32 v70, -v65, v69, v68
	v_fmac_f32_e32 v69, v70, v67
	v_fma_f32 v65, -v65, v69, v68
	v_div_fmas_f32 v65, v65, v67, v69
	v_div_fixup_f32 v64, v65, v64, 1.0
	s_and_b64 vcc, exec, s[18:19]
	s_cbranch_vccz .LBB0_291
	v_mul_f32_e32 v65, v60, v66
	v_mul_f32_e32 v67, v61, v66
	ds_write2_b32 v214, v65, v67 offset1:16
	v_mul_f32_e32 v65, v62, v66
	v_mul_f32_e32 v67, v63, v66
	ds_write2_b32 v214, v65, v67 offset0:32 offset1:48
	v_mul_f32_e32 v65, v56, v66
	v_mul_f32_e32 v67, v57, v66
	v_add_u32_e32 v68, 0x400, v214
	ds_write2_b32 v68, v65, v67 offset1:16
	v_mul_f32_e32 v65, v58, v66
	v_mul_f32_e32 v67, v59, v66
	ds_write2_b32 v68, v65, v67 offset0:32 offset1:48
	v_mul_f32_e32 v65, v52, v66
	v_mul_f32_e32 v67, v53, v66
	v_add_u32_e32 v68, 0x800, v214
	ds_write2_b32 v68, v65, v67 offset1:16
	v_mul_f32_e32 v65, v54, v66
	v_mul_f32_e32 v67, v55, v66
	ds_write2_b32 v68, v65, v67 offset0:32 offset1:48
	v_mul_f32_e32 v65, v48, v66
	v_mul_f32_e32 v67, v49, v66
	v_add_u32_e32 v68, 0xc00, v214
	ds_write2_b32 v68, v65, v67 offset1:16
	v_mul_f32_e32 v65, v50, v66
	v_mul_f32_e32 v67, v51, v66
	ds_write2_b32 v68, v65, v67 offset0:32 offset1:48
	v_mul_f32_e32 v65, v44, v66
	v_mul_f32_e32 v67, v45, v66
	v_add_u32_e32 v68, 0x1000, v214
	ds_write2_b32 v68, v65, v67 offset1:16
	v_mul_f32_e32 v65, v46, v66
	v_mul_f32_e32 v67, v47, v66
	ds_write2_b32 v68, v65, v67 offset0:32 offset1:48
	v_mul_f32_e32 v65, v40, v66
	v_mul_f32_e32 v67, v41, v66
	v_add_u32_e32 v68, 0x1400, v214
	ds_write2_b32 v68, v65, v67 offset1:16
	v_mul_f32_e32 v65, v42, v66
	v_mul_f32_e32 v67, v43, v66
	ds_write2_b32 v68, v65, v67 offset0:32 offset1:48
	v_mul_f32_e32 v65, v36, v66
	v_mul_f32_e32 v67, v37, v66
	v_add_u32_e32 v68, 0x1800, v214
	ds_write2_b32 v68, v65, v67 offset1:16
	v_mul_f32_e32 v65, v38, v66
	v_mul_f32_e32 v67, v39, v66
	ds_write2_b32 v68, v65, v67 offset0:32 offset1:48
	v_mul_f32_e32 v65, v32, v66
	v_mul_f32_e32 v67, v33, v66
	v_add_u32_e32 v68, 0x1c00, v214
	ds_write2_b32 v68, v65, v67 offset1:16
	v_mul_f32_e32 v65, v34, v66
	v_mul_f32_e32 v67, v35, v66
	ds_write2_b32 v68, v65, v67 offset0:32 offset1:48
	v_mul_f32_e32 v65, v28, v64
	v_mul_f32_e32 v67, v29, v64
	v_add_u32_e32 v68, 0x2000, v214
	ds_write2_b32 v68, v65, v67 offset1:16
	v_mul_f32_e32 v65, v30, v64
	v_mul_f32_e32 v67, v31, v64
	ds_write2_b32 v68, v65, v67 offset0:32 offset1:48
	v_mul_f32_e32 v65, v20, v64
	v_mul_f32_e32 v67, v21, v64
	v_add_u32_e32 v68, 0x2400, v214
	ds_write2_b32 v68, v65, v67 offset1:16
	v_mul_f32_e32 v65, v22, v64
	v_mul_f32_e32 v67, v23, v64
	ds_write2_b32 v68, v65, v67 offset0:32 offset1:48
	v_mul_f32_e32 v65, v24, v64
	v_mul_f32_e32 v67, v25, v64
	v_add_u32_e32 v68, 0x2800, v214
	ds_write2_b32 v68, v65, v67 offset1:16
	v_mul_f32_e32 v65, v26, v64
	v_mul_f32_e32 v67, v27, v64
	ds_write2_b32 v68, v65, v67 offset0:32 offset1:48
	v_mul_f32_e32 v65, v16, v64
	v_mul_f32_e32 v67, v17, v64
	v_add_u32_e32 v68, 0x2c00, v214
	ds_write2_b32 v68, v65, v67 offset1:16
	v_mul_f32_e32 v65, v18, v64
	v_mul_f32_e32 v67, v19, v64
	ds_write2_b32 v68, v65, v67 offset0:32 offset1:48
	v_mul_f32_e32 v65, v12, v64
	v_mul_f32_e32 v67, v13, v64
	v_add_u32_e32 v68, 0x3000, v214
	ds_write2_b32 v68, v65, v67 offset1:16
	v_mul_f32_e32 v65, v14, v64
	v_mul_f32_e32 v67, v15, v64
	ds_write2_b32 v68, v65, v67 offset0:32 offset1:48
	v_mul_f32_e32 v65, v8, v64
	v_mul_f32_e32 v67, v9, v64
	v_add_u32_e32 v68, 0x3400, v214
	ds_write2_b32 v68, v65, v67 offset1:16
	v_mul_f32_e32 v65, v10, v64
	v_mul_f32_e32 v67, v11, v64
	ds_write2_b32 v68, v65, v67 offset0:32 offset1:48
	v_mul_f32_e32 v65, v4, v64
	v_mul_f32_e32 v67, v5, v64
	v_add_u32_e32 v68, 0x3800, v214
	ds_write2_b32 v68, v65, v67 offset1:16
	v_mul_f32_e32 v65, v6, v64
	v_mul_f32_e32 v67, v7, v64
	ds_write2_b32 v68, v65, v67 offset0:32 offset1:48
	v_mul_f32_e32 v65, v0, v64
	v_mul_f32_e32 v67, v1, v64
	v_add_u32_e32 v68, 0x3c00, v214
	ds_write2_b32 v68, v65, v67 offset1:16
	v_mul_f32_e32 v65, v2, v64
	v_mul_f32_e32 v67, v3, v64
	ds_write2_b32 v68, v65, v67 offset0:32 offset1:48

; __device__ __forceinline__ int tidx() { int t = threadIdx.x; asm volatile("" : "+v"(t)); return t; }
; __global__ void __launch_bounds__(512, 2) mk_fwd(Params p) {
;     ...
;     for (int ph = p.ph_lo; ph < p.ph_hi; ++ph) {
;         const int s_ = (ph == 0) ? -1 : (ph - 1) % NPL;
;         int nrep = 1;
;         if (DUPM) { const int kind = (ph == 0) ? 0 : ((s_ == 0 || s_ == 13) ? 1 : ((s_ == 1 || s_ == 14 || s_ == 11 || s_ == 5) ? 2 : ((s_ == 2 || s_ == 12 || s_ == 15) ? 3 : ((s_ == 3) ? 4 : (s_ - 4 + 5)))));
;             if ((DUPM >> kind) & 1u) nrep = 2; }
;         for (int rep = 0; rep < nrep; ++rep) {
;         if (rep) grid.sync();
;         const int tid = tidx(), lane = tid & 63, wave = __builtin_amdgcn_readfirstlane(tid >> 6);
;         if (ph == 0) { if (PON(0)) prologue(p, lds, wave, lane); }
;         else {
;             const int l = (ph - 1) / NPL, s = (ph - 1) % NPL;
.LBB0_293:
	v_mov_b32_e32 v183, 0xc00
	v_mov_b32_e32 v192, 0xfcf
	v_not_b32_e32 v193, 63
	v_mov_b32_e32 v184, 0x358637bd
	v_mov_b32_e32 v185, 0x3a27c5ac
	v_mov_b32_e32 v186, 0x600
	v_mov_b32_e32 v187, 0x3ca908c9
	v_mov_b32_e32 v188, 0x3c0881c4
	v_mov_b32_e32 v189, 0xbab64f3b
	v_mov_b32_e32 v191, 0x1200
	v_mov_b64_e32 v[196:197], 0x560
	v_mov_b32_e32 v198, 0x3e38aa3b
	v_not_b32_e32 v199, 31
	s_and_b64 vcc, exec, s[16:17]
	s_cbranch_vccz .LBB0_308
; #define LAS __attribute__((address_space(3)))
; __device__ __forceinline__ void rwkv_combine(const Params& p, int bh, int wave, int lane, LAS unsigned char* lds) {
;     LAS float* xs = (LAS float*)lds;
;     LAS float* pw = (LAS float*)(lds + 16384 + wave * 2048);
;     const float* SEND = (const float*)(p.ws + WS_SEND) + (size_t)bh * 32 * 8192 + (size_t)(wave * 8) * 64 + lane; float* SIN = (float*)(p.ws + WS_SIN) + (size_t)bh * 32 * 4096 + (size_t)(wave * 8) * 64 + lane;
;     f32x2 s[32];
; #pragma unroll
;     for (int j = 0; j < 32; ++j) s[j] = (f32x2){0.f, 0.f};
;     float own[8], pj[4][8], sl[4][8];
; #pragma unroll
;     for (int jj = 0; jj < 8; ++jj) own[jj] = 0.f;
; #pragma unroll
;     for (int d = 0; d < 4; ++d)
; #pragma unroll
;         for (int jj = 0; jj < 8; ++jj) { pj[d][jj] = SEND[(size_t)d * 8192 + (64 + jj) * 64]; sl[d][jj] = SEND[(size_t)d * 8192 + jj * 64]; }
	s_mov_b32 s6, s2
	s_lshl_b32 s18, s34, 11
	s_ashr_i32 s7, s6, 31
	s_lshl_b32 s14, s34, 3
	s_add_i32 s19, s18, 0
	s_lshl_b64 s[12:13], s[6:7], 20
	s_ashr_i32 s15, s14, 31
	s_lshl_b64 s[6:7], s[6:7], 19
	v_readlane_b32 s3, v251, 62
	s_add_u32 s16, s3, s12
	v_readlane_b32 s3, v251, 63
	s_addc_u32 s17, s3, s13
	s_lshl_b64 s[14:15], s[14:15], 8
	s_add_u32 s16, s16, s14
	s_addc_u32 s17, s17, s15
	v_lshlrev_b32_e32 v136, 2, v151
	v_lshl_add_u64 v[0:1], s[16:17], 0, v[136:137]
	s_movk_i32 s3, 0x4000
	v_add_co_u32_e32 v2, vcc, s3, v0
	s_mov_b32 s3, 0xc000
	s_nop 0
	v_addc_co_u32_e32 v3, vcc, 0, v1, vcc
	global_load_dword v82, v[2:3], off
	global_load_dword v83, v[2:3], off offset:256
	global_load_dword v84, v[2:3], off offset:512
	global_load_dword v85, v[2:3], off offset:768
	global_load_dword v86, v[2:3], off offset:1024
	global_load_dword v87, v[2:3], off offset:1280
	global_load_dword v88, v[2:3], off offset:1536
	global_load_dword v89, v[2:3], off offset:1792
	global_load_dword v124, v136, s[16:17]
	global_load_dword v131, v136, s[16:17] offset:256
	global_load_dword v130, v136, s[16:17] offset:512
	global_load_dword v129, v136, s[16:17] offset:768
	global_load_dword v128, v136, s[16:17] offset:1024
	global_load_dword v127, v136, s[16:17] offset:1280
	global_load_dword v126, v136, s[16:17] offset:1536
	global_load_dword v125, v136, s[16:17] offset:1792
	v_add_co_u32_e32 v2, vcc, s3, v0
	s_mov_b32 s3, 0x8000
	s_nop 0
	v_addc_co_u32_e32 v3, vcc, 0, v1, vcc
	v_add_co_u32_e32 v4, vcc, s3, v0
	s_mov_b32 s3, 0x14000
	s_nop 0
	v_addc_co_u32_e32 v5, vcc, 0, v1, vcc
	global_load_dword v90, v[2:3], off
	global_load_dword v91, v[2:3], off offset:256
	global_load_dword v92, v[2:3], off offset:512
	global_load_dword v93, v[2:3], off offset:768
	global_load_dword v94, v[2:3], off offset:1024
	global_load_dword v95, v[2:3], off offset:1280
	global_load_dword v96, v[2:3], off offset:1536
	global_load_dword v97, v[2:3], off offset:1792
	global_load_dword v148, v[4:5], off
	global_load_dword v147, v[4:5], off offset:256
	global_load_dword v146, v[4:5], off offset:512
	global_load_dword v145, v[4:5], off offset:768
	global_load_dword v144, v[4:5], off offset:1024
	global_load_dword v135, v[4:5], off offset:1280
	global_load_dword v134, v[4:5], off offset:1536
	global_load_dword v133, v[4:5], off offset:1792
	v_add_co_u32_e32 v2, vcc, s3, v0
	s_mov_b32 s3, 0x10000
	s_nop 0
	v_addc_co_u32_e32 v3, vcc, 0, v1, vcc
	v_add_co_u32_e32 v4, vcc, s3, v0
	s_mov_b32 s3, 0x1c000
	s_nop 0
	v_addc_co_u32_e32 v5, vcc, 0, v1, vcc
	global_load_dword v98, v[2:3], off
	global_load_dword v99, v[2:3], off offset:256
	global_load_dword v100, v[2:3], off offset:512
	global_load_dword v101, v[2:3], off offset:768
	global_load_dword v102, v[2:3], off offset:1024
	global_load_dword v103, v[2:3], off offset:1280
	global_load_dword v104, v[2:3], off offset:1536
	global_load_dword v105, v[2:3], off offset:1792
	global_load_dword v156, v[4:5], off
	global_load_dword v155, v[4:5], off offset:256
	global_load_dword v154, v[4:5], off offset:512
	global_load_dword v153, v[4:5], off offset:768
	global_load_dword v152, v[4:5], off offset:1024
	global_load_dword v151, v[4:5], off offset:1280
	global_load_dword v150, v[4:5], off offset:1536
	global_load_dword v149, v[4:5], off offset:1792
	v_add_co_u32_e32 v2, vcc, s3, v0
	s_mov_b32 s3, 0x18000
	s_nop 0
	v_addc_co_u32_e32 v3, vcc, 0, v1, vcc
	v_add_co_u32_e32 v8, vcc, s3, v0
	s_add_u32 s12, s12, s14
	s_nop 0
	v_addc_co_u32_e32 v9, vcc, 0, v1, vcc
	global_load_dword v106, v[2:3], off
	global_load_dword v107, v[2:3], off offset:256
	global_load_dword v108, v[2:3], off offset:512
	global_load_dword v111, v[2:3], off offset:768
	global_load_dword v112, v[2:3], off offset:1024
	global_load_dword v113, v[2:3], off offset:1280
	global_load_dword v114, v[2:3], off offset:1536
	global_load_dword v115, v[2:3], off offset:1792
	global_load_dword v7, v[8:9], off
	global_load_dword v6, v[8:9], off offset:256
	global_load_dword v5, v[8:9], off offset:512
	global_load_dword v4, v[8:9], off offset:768
	s_nop 0
	global_load_dword v3, v[8:9], off offset:1024
	global_load_dword v2, v[8:9], off offset:1280
	global_load_dword v1, v[8:9], off offset:1536
	global_load_dword v0, v[8:9], off offset:1792
	v_readlane_b32 s24, v252, 40
	s_addc_u32 s13, s13, s15
	v_readlane_b32 s26, v252, 42
	v_readlane_b32 s27, v252, 43
	s_add_u32 s12, s26, s12
	s_addc_u32 s13, s27, s13
	s_add_u32 s6, s6, s14
	s_addc_u32 s7, s7, s15
	s_add_u32 s14, s26, s6
	v_mov_b32_e32 v10, 0
	s_mov_b32 s20, 0
	s_waitcnt vmcnt(0)
	v_add_u32_e32 v109, s19, v136
	v_add_u32_e32 v110, 0, v136
	s_addc_u32 s15, s27, s7
	v_mov_b32_e32 v11, v10
	v_mov_b32_e32 v12, v10
	v_mov_b32_e32 v13, v10
	v_mov_b32_e32 v14, v10
	v_mov_b32_e32 v15, v10
	v_mov_b32_e32 v16, v10
	v_mov_b32_e32 v17, v10
	v_mov_b32_e32 v18, v10
	v_mov_b32_e32 v19, v10
	v_mov_b32_e32 v20, v10
	v_mov_b32_e32 v21, v10
	v_mov_b32_e32 v22, v10
	v_mov_b32_e32 v23, v10
	v_mov_b32_e32 v24, v10
	v_mov_b32_e32 v25, v10
	v_mov_b32_e32 v26, v10
	v_mov_b32_e32 v27, v10
	v_mov_b32_e32 v28, v10
	v_mov_b32_e32 v29, v10
	v_mov_b32_e32 v30, v10
	v_mov_b32_e32 v31, v10
	v_mov_b32_e32 v32, v10
	v_mov_b32_e32 v33, v10
	v_mov_b32_e32 v34, v10
	v_mov_b32_e32 v35, v10
	v_mov_b32_e32 v36, v10
	v_mov_b32_e32 v37, v10
	v_mov_b32_e32 v38, v10
	v_mov_b32_e32 v39, v10
	v_mov_b32_e32 v40, v10
	v_mov_b32_e32 v41, v10
	v_mov_b32_e32 v42, v10
	v_mov_b32_e32 v43, v10
	v_mov_b32_e32 v44, v10
	v_mov_b32_e32 v45, v10
	v_mov_b32_e32 v46, v10
	v_mov_b32_e32 v47, v10
	v_mov_b32_e32 v48, v10
	v_mov_b32_e32 v49, v10
	v_mov_b32_e32 v50, v10
	v_mov_b32_e32 v51, v10
	v_mov_b32_e32 v52, v10
	v_mov_b32_e32 v53, v10
	v_mov_b32_e32 v54, v10
	v_mov_b32_e32 v55, v10
	v_mov_b32_e32 v56, v10
	v_mov_b32_e32 v57, v10
	v_mov_b32_e32 v58, v10
	v_mov_b32_e32 v59, v10
	v_mov_b32_e32 v60, v10
	v_mov_b32_e32 v61, v10
	v_mov_b32_e32 v62, v10
	v_mov_b32_e32 v63, v10
	v_mov_b32_e32 v64, v10
	v_mov_b32_e32 v65, v10
	v_mov_b32_e32 v66, v10
	v_mov_b32_e32 v67, v10
	v_mov_b32_e32 v68, v10
	v_mov_b32_e32 v69, v10
	v_mov_b32_e32 v70, v10
	v_mov_b32_e32 v71, v10
	v_mov_b32_e32 v72, v10
	v_mov_b32_e32 v73, v10
	v_mov_b32_e32 v80, v10
	v_mov_b32_e32 v81, v10
	v_mov_b32_e32 v78, v10
	v_mov_b32_e32 v79, v10
	v_mov_b32_e32 v76, v10
	v_mov_b32_e32 v77, v10
	v_mov_b32_e32 v74, v10
	v_mov_b32_e32 v75, v10
	s_waitcnt vmcnt(48)
	v_mov_b32_e32 v116, v125
	v_mov_b32_e32 v117, v126
	v_mov_b32_e32 v118, v127
	v_mov_b32_e32 v119, v128
	v_mov_b32_e32 v120, v129
	v_mov_b32_e32 v121, v130
	v_mov_b32_e32 v122, v131
	v_mov_b32_e32 v123, v124
	v_readlane_b32 s25, v252, 41
	s_branch .LBB0_296

; __global__ void __launch_bounds__(512, 2) mk_fwd(Params p) {
;     extern __shared__ __attribute__((aligned(16))) unsigned char smem[];
	.amdhsa_kernel _Z6mk_fwd6Params
		.amdhsa_group_segment_fixed_size 0
		.amdhsa_private_segment_fixed_size 0
		.amdhsa_kernarg_size 592
		.amdhsa_user_sgpr_count 2
		.amdhsa_user_sgpr_dispatch_ptr 0
		.amdhsa_user_sgpr_queue_ptr 0
		.amdhsa_user_sgpr_kernarg_segment_ptr 1
		.amdhsa_user_sgpr_dispatch_id 0
		.amdhsa_user_sgpr_kernarg_preload_length 0
		.amdhsa_user_sgpr_kernarg_preload_offset 0
		.amdhsa_user_sgpr_private_segment_size 0
		.amdhsa_uses_dynamic_stack 0
		.amdhsa_enable_private_segment 0
		.amdhsa_system_sgpr_workgroup_id_x 1
		.amdhsa_system_sgpr_workgroup_id_y 0
		.amdhsa_system_sgpr_workgroup_id_z 0
		.amdhsa_system_sgpr_workgroup_info 0
		.amdhsa_system_vgpr_workitem_id 2
		.amdhsa_next_free_vgpr 256
		.amdhsa_next_free_sgpr 102
		.amdhsa_accum_offset 256
		.amdhsa_reserve_vcc 1
		.amdhsa_float_round_mode_32 0
		.amdhsa_float_round_mode_16_64 0
		.amdhsa_float_denorm_mode_32 3
		.amdhsa_float_denorm_mode_16_64 3
		.amdhsa_dx10_clamp 1
		.amdhsa_ieee_mode 1
		.amdhsa_fp16_overflow 0
		.amdhsa_tg_split 0
		.amdhsa_exception_fp_ieee_invalid_op 0
		.amdhsa_exception_fp_denorm_src 0
		.amdhsa_exception_fp_ieee_div_zero 0
		.amdhsa_exception_fp_ieee_overflow 0
		.amdhsa_exception_fp_ieee_underflow 0
		.amdhsa_exception_fp_ieee_inexact 0
		.amdhsa_exception_int_div_zero 0
	.end_amdhsa_kernel

; __global__ void __launch_bounds__(512, 2) mk_fwd(Params p) {
;     extern __shared__ __attribute__((aligned(16))) unsigned char smem[];
amdhsa.kernels:
  - .agpr_count:     0
    .args:
      - .offset:         0
        .size:           336
        .value_kind:     by_value
      - .offset:         336
        .size:           4
        .value_kind:     hidden_block_count_x
      - .offset:         340
        .size:           4
        .value_kind:     hidden_block_count_y
      - .offset:         344
        .size:           4
        .value_kind:     hidden_block_count_z
      - .offset:         348
        .size:           2
        .value_kind:     hidden_group_size_x
      - .offset:         350
        .size:           2
        .value_kind:     hidden_group_size_y
      - .offset:         352
        .size:           2
        .value_kind:     hidden_group_size_z
      - .offset:         354
        .size:           2
        .value_kind:     hidden_remainder_x
      - .offset:         356
        .size:           2
        .value_kind:     hidden_remainder_y
      - .offset:         358
        .size:           2
        .value_kind:     hidden_remainder_z
      - .offset:         376
        .size:           8
        .value_kind:     hidden_global_offset_x
      - .offset:         384
        .size:           8
        .value_kind:     hidden_global_offset_y
      - .offset:         392
        .size:           8
        .value_kind:     hidden_global_offset_z
      - .offset:         400
        .size:           2
        .value_kind:     hidden_grid_dims
      - .offset:         424
        .size:           8
        .value_kind:     hidden_multigrid_sync_arg
      - .offset:         456
        .size:           4
        .value_kind:     hidden_dynamic_lds_size
    .group_segment_fixed_size: 0
    .kernarg_segment_align: 8
    .kernarg_segment_size: 592
    .language:       OpenCL C
    .language_version:
      - 2
      - 0
    .max_flat_workgroup_size: 512
    .name:           _Z6mk_fwd6Params
    .private_segment_fixed_size: 0
    .sgpr_count:     108
    .sgpr_spill_count: 325
    .symbol:         _Z6mk_fwd6Params.kd
    .uniform_work_group_size: 1
    .uses_dynamic_stack: false
    .vgpr_count:     256
    .vgpr_spill_count: 0
    .wavefront_size: 64
